# also: WKV scan recurrence loop rewritten with packed f32 FMAs (v_pk_fma_f32, same f32 arithmetic), and the chunk preparation of the producer waves software-pipelined across two barrier intervals (firs
# speedup vs baseline: 1.0707x; 1.0274x over previous
.LBB0_1112:
	s_and_b32 s11, s10, 1
	s_mul_i32 s18, s11, 0x4e00
	s_waitcnt vmcnt(0)
	v_lshl_add_u32 v131, s11, 14, v21
	v_lshl_add_u32 v130, v20, 2, s18
	v_mov_b32_e32 v129, s18
	v_lshl_add_u32 v128, v16, 2, s18
	s_add_i32 s10, s10, 1
	ds_read_b128 v[44:47], v130 offset:0
	ds_read_b128 v[48:51], v130 offset:256
	ds_read_b128 v[52:55], v130 offset:512
	ds_read_b128 v[56:59], v130 offset:768
	ds_read_b128 v[60:63], v130 offset:1024
	ds_read_b128 v[64:67], v130 offset:1280
	ds_read_b128 v[68:71], v130 offset:1536
	ds_read_b128 v[72:75], v130 offset:1792
	ds_read_b128 v[76:79], v130 offset:2048
	ds_read_b128 v[80:83], v129 offset:2432
	ds_read_b128 v[84:87], v129 offset:2448
	ds_read_b32 v89, v128 offset:2304
	ds_read_b32 v91, v128 offset:2368
	ds_read_b128 v[196:199], v130 offset:2496
	ds_read_b128 v[200:203], v130 offset:2752
	ds_read_b128 v[204:207], v130 offset:3008
	ds_read_b128 v[208:211], v130 offset:3264
	ds_read_b128 v[212:215], v130 offset:3520
	ds_read_b128 v[216:219], v130 offset:3776
	ds_read_b128 v[220:223], v130 offset:4032
	ds_read_b128 v[224:227], v130 offset:4288
	ds_read_b128 v[228:231], v130 offset:4544
	ds_read_b128 v[232:235], v129 offset:4928
	ds_read_b128 v[236:239], v129 offset:4944
	ds_read_b32 v241, v128 offset:4800
	ds_read_b32 v243, v128 offset:4864
	s_waitcnt lgkmcnt(13)
	v_pk_mul_f32 v[4:5], v[0:1], v[44:45]
	v_pk_mul_f32 v[6:7], v[0:1], v[48:49]
	v_pk_fma_f32 v[4:5], v[2:3], v[46:47], v[4:5]
	v_pk_fma_f32 v[6:7], v[2:3], v[50:51], v[6:7]
	v_add_f32_e32 v22, v4, v5
	v_add_f32_e32 v42, v6, v7
	v_pk_mul_f32 v[8:9], v[0:1], v[52:53]
	v_add_f32_dpp v22, v22, v22 quad_perm:[1,0,3,2] row_mask:0xf bank_mask:0xf bound_ctrl:1
	v_add_f32_dpp v42, v42, v42 quad_perm:[1,0,3,2] row_mask:0xf bank_mask:0xf bound_ctrl:1
	v_pk_mul_f32 v[10:11], v[2:3], v[54:55]
	v_add_f32_dpp v22, v22, v22 quad_perm:[2,3,0,1] row_mask:0xf bank_mask:0xf bound_ctrl:1
	v_add_f32_dpp v42, v42, v42 quad_perm:[2,3,0,1] row_mask:0xf bank_mask:0xf bound_ctrl:1
	v_pk_mul_f32 v[12:13], v[0:1], v[72:73]
	v_add_f32_dpp v22, v22, v22 row_ror:4 row_mask:0xf bank_mask:0xf bound_ctrl:1
	v_add_f32_dpp v42, v42, v42 row_ror:4 row_mask:0xf bank_mask:0xf bound_ctrl:1
	v_pk_mul_f32 v[14:15], v[0:1], v[76:77]
	v_add_f32_dpp v88, v22, v22 row_ror:8 row_mask:0xf bank_mask:0xf bound_ctrl:1
	v_add_f32_dpp v42, v42, v42 row_ror:8 row_mask:0xf bank_mask:0xf bound_ctrl:1
	v_pk_fma_f32 v[8:9], v[88:89], v[60:61], v[8:9] op_sel:[1,0,0] op_sel_hi:[1,1,1]
	v_pk_fma_f32 v[10:11], v[88:89], v[62:63], v[10:11] op_sel:[1,0,0] op_sel_hi:[1,1,1]
	v_fma_f32 v4, v88, v80, v42
	v_pk_fma_f32 v[8:9], v[90:91], v[68:69], v[8:9] op_sel:[1,0,0] op_sel_hi:[1,1,1]
	v_fma_f32 v90, v89, v81, v4
	v_pk_fma_f32 v[10:11], v[90:91], v[70:71], v[10:11] op_sel:[1,0,0] op_sel_hi:[1,1,1]
	v_pk_fma_f32 v[12:13], v[2:3], v[74:75], v[12:13]
	v_pk_fma_f32 v[14:15], v[2:3], v[78:79], v[14:15]
	v_pk_fma_f32 v[0:1], v[88:89], v[56:57], v[8:9] op_sel:[0,0,0] op_sel_hi:[0,1,1]
	v_pk_fma_f32 v[2:3], v[88:89], v[58:59], v[10:11] op_sel:[0,0,0] op_sel_hi:[0,1,1]
	v_pk_fma_f32 v[0:1], v[90:91], v[64:65], v[0:1] op_sel:[0,0,0] op_sel_hi:[0,1,1]
	v_pk_fma_f32 v[2:3], v[90:91], v[66:67], v[2:3] op_sel:[0,0,0] op_sel_hi:[0,1,1]
	v_pk_fma_f32 v[12:13], v[88:89], v[82:83], v[12:13]
	v_pk_fma_f32 v[14:15], v[90:91], v[86:87], v[14:15]
	v_pk_fma_f32 v[14:15], v[88:89], v[84:85], v[14:15]
	v_add_f32_e32 v6, v12, v13
	v_add_f32_e32 v7, v14, v15
	ds_write2st64_b32 v131, v6, v7 offset0:156 offset1:160
	ds_read_b128 v[44:47], v130 offset:4992
	ds_read_b128 v[48:51], v130 offset:5248
	ds_read_b128 v[52:55], v130 offset:5504
	ds_read_b128 v[56:59], v130 offset:5760
	ds_read_b128 v[60:63], v130 offset:6016
	ds_read_b128 v[64:67], v130 offset:6272
	ds_read_b128 v[68:71], v130 offset:6528
	ds_read_b128 v[72:75], v130 offset:6784
	ds_read_b128 v[76:79], v130 offset:7040
	ds_read_b128 v[80:83], v129 offset:7424
	ds_read_b128 v[84:87], v129 offset:7440
	ds_read_b32 v89, v128 offset:7296
	ds_read_b32 v91, v128 offset:7360
	s_waitcnt lgkmcnt(13)
	v_pk_mul_f32 v[4:5], v[0:1], v[196:197]
	v_pk_mul_f32 v[6:7], v[0:1], v[200:201]
	v_pk_fma_f32 v[4:5], v[2:3], v[198:199], v[4:5]
	v_pk_fma_f32 v[6:7], v[2:3], v[202:203], v[6:7]
	v_add_f32_e32 v22, v4, v5
	v_add_f32_e32 v42, v6, v7
	v_pk_mul_f32 v[8:9], v[0:1], v[204:205]
	v_add_f32_dpp v22, v22, v22 quad_perm:[1,0,3,2] row_mask:0xf bank_mask:0xf bound_ctrl:1
	v_add_f32_dpp v42, v42, v42 quad_perm:[1,0,3,2] row_mask:0xf bank_mask:0xf bound_ctrl:1
	v_pk_mul_f32 v[10:11], v[2:3], v[206:207]
	v_add_f32_dpp v22, v22, v22 quad_perm:[2,3,0,1] row_mask:0xf bank_mask:0xf bound_ctrl:1
	v_add_f32_dpp v42, v42, v42 quad_perm:[2,3,0,1] row_mask:0xf bank_mask:0xf bound_ctrl:1
	v_pk_mul_f32 v[12:13], v[0:1], v[224:225]
	v_add_f32_dpp v22, v22, v22 row_ror:4 row_mask:0xf bank_mask:0xf bound_ctrl:1
	v_add_f32_dpp v42, v42, v42 row_ror:4 row_mask:0xf bank_mask:0xf bound_ctrl:1
	v_pk_mul_f32 v[14:15], v[0:1], v[228:229]
	v_add_f32_dpp v240, v22, v22 row_ror:8 row_mask:0xf bank_mask:0xf bound_ctrl:1
	v_add_f32_dpp v42, v42, v42 row_ror:8 row_mask:0xf bank_mask:0xf bound_ctrl:1
	v_pk_fma_f32 v[8:9], v[240:241], v[212:213], v[8:9] op_sel:[1,0,0] op_sel_hi:[1,1,1]
	v_pk_fma_f32 v[10:11], v[240:241], v[214:215], v[10:11] op_sel:[1,0,0] op_sel_hi:[1,1,1]
	v_fma_f32 v4, v240, v232, v42
	v_pk_fma_f32 v[8:9], v[242:243], v[220:221], v[8:9] op_sel:[1,0,0] op_sel_hi:[1,1,1]
	v_fma_f32 v242, v241, v233, v4
	v_pk_fma_f32 v[10:11], v[242:243], v[222:223], v[10:11] op_sel:[1,0,0] op_sel_hi:[1,1,1]
	v_pk_fma_f32 v[12:13], v[2:3], v[226:227], v[12:13]
	v_pk_fma_f32 v[14:15], v[2:3], v[230:231], v[14:15]
	v_pk_fma_f32 v[0:1], v[240:241], v[208:209], v[8:9] op_sel:[0,0,0] op_sel_hi:[0,1,1]
	v_pk_fma_f32 v[2:3], v[240:241], v[210:211], v[10:11] op_sel:[0,0,0] op_sel_hi:[0,1,1]
	v_pk_fma_f32 v[0:1], v[242:243], v[216:217], v[0:1] op_sel:[0,0,0] op_sel_hi:[0,1,1]
	v_pk_fma_f32 v[2:3], v[242:243], v[218:219], v[2:3] op_sel:[0,0,0] op_sel_hi:[0,1,1]
	v_pk_fma_f32 v[12:13], v[240:241], v[234:235], v[12:13]
	v_pk_fma_f32 v[14:15], v[242:243], v[238:239], v[14:15]
	v_pk_fma_f32 v[14:15], v[240:241], v[236:237], v[14:15]
	v_add_f32_e32 v6, v12, v13
	v_add_f32_e32 v7, v14, v15
	ds_write2st64_b32 v131, v6, v7 offset0:164 offset1:168
	ds_read_b128 v[196:199], v130 offset:7488
	ds_read_b128 v[200:203], v130 offset:7744
	ds_read_b128 v[204:207], v130 offset:8000
	ds_read_b128 v[208:211], v130 offset:8256
	ds_read_b128 v[212:215], v130 offset:8512
	ds_read_b128 v[216:219], v130 offset:8768
	ds_read_b128 v[220:223], v130 offset:9024
	ds_read_b128 v[224:227], v130 offset:9280
	ds_read_b128 v[228:231], v130 offset:9536
	ds_read_b128 v[232:235], v129 offset:9920
	ds_read_b128 v[236:239], v129 offset:9936
	ds_read_b32 v241, v128 offset:9792
	ds_read_b32 v243, v128 offset:9856
	s_waitcnt lgkmcnt(13)
	v_pk_mul_f32 v[4:5], v[0:1], v[44:45]
	v_pk_mul_f32 v[6:7], v[0:1], v[48:49]
	v_pk_fma_f32 v[4:5], v[2:3], v[46:47], v[4:5]
	v_pk_fma_f32 v[6:7], v[2:3], v[50:51], v[6:7]
	v_add_f32_e32 v22, v4, v5
	v_add_f32_e32 v42, v6, v7
	v_pk_mul_f32 v[8:9], v[0:1], v[52:53]
	v_add_f32_dpp v22, v22, v22 quad_perm:[1,0,3,2] row_mask:0xf bank_mask:0xf bound_ctrl:1
	v_add_f32_dpp v42, v42, v42 quad_perm:[1,0,3,2] row_mask:0xf bank_mask:0xf bound_ctrl:1
	v_pk_mul_f32 v[10:11], v[2:3], v[54:55]
	v_add_f32_dpp v22, v22, v22 quad_perm:[2,3,0,1] row_mask:0xf bank_mask:0xf bound_ctrl:1
	v_add_f32_dpp v42, v42, v42 quad_perm:[2,3,0,1] row_mask:0xf bank_mask:0xf bound_ctrl:1
	v_pk_mul_f32 v[12:13], v[0:1], v[72:73]
	v_add_f32_dpp v22, v22, v22 row_ror:4 row_mask:0xf bank_mask:0xf bound_ctrl:1
	v_add_f32_dpp v42, v42, v42 row_ror:4 row_mask:0xf bank_mask:0xf bound_ctrl:1
	v_pk_mul_f32 v[14:15], v[0:1], v[76:77]
	v_add_f32_dpp v88, v22, v22 row_ror:8 row_mask:0xf bank_mask:0xf bound_ctrl:1
	v_add_f32_dpp v42, v42, v42 row_ror:8 row_mask:0xf bank_mask:0xf bound_ctrl:1
	v_pk_fma_f32 v[8:9], v[88:89], v[60:61], v[8:9] op_sel:[1,0,0] op_sel_hi:[1,1,1]
	v_pk_fma_f32 v[10:11], v[88:89], v[62:63], v[10:11] op_sel:[1,0,0] op_sel_hi:[1,1,1]
	v_fma_f32 v4, v88, v80, v42
	v_pk_fma_f32 v[8:9], v[90:91], v[68:69], v[8:9] op_sel:[1,0,0] op_sel_hi:[1,1,1]
	v_fma_f32 v90, v89, v81, v4
	v_pk_fma_f32 v[10:11], v[90:91], v[70:71], v[10:11] op_sel:[1,0,0] op_sel_hi:[1,1,1]
	v_pk_fma_f32 v[12:13], v[2:3], v[74:75], v[12:13]
	v_pk_fma_f32 v[14:15], v[2:3], v[78:79], v[14:15]
	v_pk_fma_f32 v[0:1], v[88:89], v[56:57], v[8:9] op_sel:[0,0,0] op_sel_hi:[0,1,1]
	v_pk_fma_f32 v[2:3], v[88:89], v[58:59], v[10:11] op_sel:[0,0,0] op_sel_hi:[0,1,1]
	v_pk_fma_f32 v[0:1], v[90:91], v[64:65], v[0:1] op_sel:[0,0,0] op_sel_hi:[0,1,1]
	v_pk_fma_f32 v[2:3], v[90:91], v[66:67], v[2:3] op_sel:[0,0,0] op_sel_hi:[0,1,1]
	v_pk_fma_f32 v[12:13], v[88:89], v[82:83], v[12:13]
	v_pk_fma_f32 v[14:15], v[90:91], v[86:87], v[14:15]
	v_pk_fma_f32 v[14:15], v[88:89], v[84:85], v[14:15]
	v_add_f32_e32 v6, v12, v13
	v_add_f32_e32 v7, v14, v15
	ds_write2st64_b32 v131, v6, v7 offset0:172 offset1:176
	ds_read_b128 v[44:47], v130 offset:9984
	ds_read_b128 v[48:51], v130 offset:10240
	ds_read_b128 v[52:55], v130 offset:10496
	ds_read_b128 v[56:59], v130 offset:10752
	ds_read_b128 v[60:63], v130 offset:11008
	ds_read_b128 v[64:67], v130 offset:11264
	ds_read_b128 v[68:71], v130 offset:11520
	ds_read_b128 v[72:75], v130 offset:11776
	ds_read_b128 v[76:79], v130 offset:12032
	ds_read_b128 v[80:83], v129 offset:12416
	ds_read_b128 v[84:87], v129 offset:12432
	ds_read_b32 v89, v128 offset:12288
	ds_read_b32 v91, v128 offset:12352
	s_waitcnt lgkmcnt(13)
	v_pk_mul_f32 v[4:5], v[0:1], v[196:197]
	v_pk_mul_f32 v[6:7], v[0:1], v[200:201]
	v_pk_fma_f32 v[4:5], v[2:3], v[198:199], v[4:5]
	v_pk_fma_f32 v[6:7], v[2:3], v[202:203], v[6:7]
	v_add_f32_e32 v22, v4, v5
	v_add_f32_e32 v42, v6, v7
	v_pk_mul_f32 v[8:9], v[0:1], v[204:205]
	v_add_f32_dpp v22, v22, v22 quad_perm:[1,0,3,2] row_mask:0xf bank_mask:0xf bound_ctrl:1
	v_add_f32_dpp v42, v42, v42 quad_perm:[1,0,3,2] row_mask:0xf bank_mask:0xf bound_ctrl:1
	v_pk_mul_f32 v[10:11], v[2:3], v[206:207]
	v_add_f32_dpp v22, v22, v22 quad_perm:[2,3,0,1] row_mask:0xf bank_mask:0xf bound_ctrl:1
	v_add_f32_dpp v42, v42, v42 quad_perm:[2,3,0,1] row_mask:0xf bank_mask:0xf bound_ctrl:1
	v_pk_mul_f32 v[12:13], v[0:1], v[224:225]
	v_add_f32_dpp v22, v22, v22 row_ror:4 row_mask:0xf bank_mask:0xf bound_ctrl:1
	v_add_f32_dpp v42, v42, v42 row_ror:4 row_mask:0xf bank_mask:0xf bound_ctrl:1
	v_pk_mul_f32 v[14:15], v[0:1], v[228:229]
	v_add_f32_dpp v240, v22, v22 row_ror:8 row_mask:0xf bank_mask:0xf bound_ctrl:1
	v_add_f32_dpp v42, v42, v42 row_ror:8 row_mask:0xf bank_mask:0xf bound_ctrl:1
	v_pk_fma_f32 v[8:9], v[240:241], v[212:213], v[8:9] op_sel:[1,0,0] op_sel_hi:[1,1,1]
	v_pk_fma_f32 v[10:11], v[240:241], v[214:215], v[10:11] op_sel:[1,0,0] op_sel_hi:[1,1,1]
	v_fma_f32 v4, v240, v232, v42
	v_pk_fma_f32 v[8:9], v[242:243], v[220:221], v[8:9] op_sel:[1,0,0] op_sel_hi:[1,1,1]
	v_fma_f32 v242, v241, v233, v4
	v_pk_fma_f32 v[10:11], v[242:243], v[222:223], v[10:11] op_sel:[1,0,0] op_sel_hi:[1,1,1]
	v_pk_fma_f32 v[12:13], v[2:3], v[226:227], v[12:13]
	v_pk_fma_f32 v[14:15], v[2:3], v[230:231], v[14:15]
	v_pk_fma_f32 v[0:1], v[240:241], v[208:209], v[8:9] op_sel:[0,0,0] op_sel_hi:[0,1,1]
	v_pk_fma_f32 v[2:3], v[240:241], v[210:211], v[10:11] op_sel:[0,0,0] op_sel_hi:[0,1,1]
	v_pk_fma_f32 v[0:1], v[242:243], v[216:217], v[0:1] op_sel:[0,0,0] op_sel_hi:[0,1,1]
	v_pk_fma_f32 v[2:3], v[242:243], v[218:219], v[2:3] op_sel:[0,0,0] op_sel_hi:[0,1,1]
	v_pk_fma_f32 v[12:13], v[240:241], v[234:235], v[12:13]
	v_pk_fma_f32 v[14:15], v[242:243], v[238:239], v[14:15]
	v_pk_fma_f32 v[14:15], v[240:241], v[236:237], v[14:15]
	v_add_f32_e32 v6, v12, v13
	v_add_f32_e32 v7, v14, v15
	ds_write2st64_b32 v131, v6, v7 offset0:180 offset1:184
	ds_read_b128 v[196:199], v130 offset:12480
	ds_read_b128 v[200:203], v130 offset:12736
	ds_read_b128 v[204:207], v130 offset:12992
	ds_read_b128 v[208:211], v130 offset:13248
	ds_read_b128 v[212:215], v130 offset:13504
	ds_read_b128 v[216:219], v130 offset:13760
	ds_read_b128 v[220:223], v130 offset:14016
	ds_read_b128 v[224:227], v130 offset:14272
	ds_read_b128 v[228:231], v130 offset:14528
	ds_read_b128 v[232:235], v129 offset:14912
	ds_read_b128 v[236:239], v129 offset:14928
	ds_read_b32 v241, v128 offset:14784
	ds_read_b32 v243, v128 offset:14848
	s_waitcnt lgkmcnt(13)
	v_pk_mul_f32 v[4:5], v[0:1], v[44:45]
	v_pk_mul_f32 v[6:7], v[0:1], v[48:49]
	v_pk_fma_f32 v[4:5], v[2:3], v[46:47], v[4:5]
	v_pk_fma_f32 v[6:7], v[2:3], v[50:51], v[6:7]
	v_add_f32_e32 v22, v4, v5
	v_add_f32_e32 v42, v6, v7
	v_pk_mul_f32 v[8:9], v[0:1], v[52:53]
	v_add_f32_dpp v22, v22, v22 quad_perm:[1,0,3,2] row_mask:0xf bank_mask:0xf bound_ctrl:1
	v_add_f32_dpp v42, v42, v42 quad_perm:[1,0,3,2] row_mask:0xf bank_mask:0xf bound_ctrl:1
	v_pk_mul_f32 v[10:11], v[2:3], v[54:55]
	v_add_f32_dpp v22, v22, v22 quad_perm:[2,3,0,1] row_mask:0xf bank_mask:0xf bound_ctrl:1
	v_add_f32_dpp v42, v42, v42 quad_perm:[2,3,0,1] row_mask:0xf bank_mask:0xf bound_ctrl:1
	v_pk_mul_f32 v[12:13], v[0:1], v[72:73]
	v_add_f32_dpp v22, v22, v22 row_ror:4 row_mask:0xf bank_mask:0xf bound_ctrl:1
	v_add_f32_dpp v42, v42, v42 row_ror:4 row_mask:0xf bank_mask:0xf bound_ctrl:1
	v_pk_mul_f32 v[14:15], v[0:1], v[76:77]
	v_add_f32_dpp v88, v22, v22 row_ror:8 row_mask:0xf bank_mask:0xf bound_ctrl:1
	v_add_f32_dpp v42, v42, v42 row_ror:8 row_mask:0xf bank_mask:0xf bound_ctrl:1
	v_pk_fma_f32 v[8:9], v[88:89], v[60:61], v[8:9] op_sel:[1,0,0] op_sel_hi:[1,1,1]
	v_pk_fma_f32 v[10:11], v[88:89], v[62:63], v[10:11] op_sel:[1,0,0] op_sel_hi:[1,1,1]
	v_fma_f32 v4, v88, v80, v42
	v_pk_fma_f32 v[8:9], v[90:91], v[68:69], v[8:9] op_sel:[1,0,0] op_sel_hi:[1,1,1]
	v_fma_f32 v90, v89, v81, v4
	v_pk_fma_f32 v[10:11], v[90:91], v[70:71], v[10:11] op_sel:[1,0,0] op_sel_hi:[1,1,1]
	v_pk_fma_f32 v[12:13], v[2:3], v[74:75], v[12:13]
	v_pk_fma_f32 v[14:15], v[2:3], v[78:79], v[14:15]
	v_pk_fma_f32 v[0:1], v[88:89], v[56:57], v[8:9] op_sel:[0,0,0] op_sel_hi:[0,1,1]
	v_pk_fma_f32 v[2:3], v[88:89], v[58:59], v[10:11] op_sel:[0,0,0] op_sel_hi:[0,1,1]
	v_pk_fma_f32 v[0:1], v[90:91], v[64:65], v[0:1] op_sel:[0,0,0] op_sel_hi:[0,1,1]
	v_pk_fma_f32 v[2:3], v[90:91], v[66:67], v[2:3] op_sel:[0,0,0] op_sel_hi:[0,1,1]
	v_pk_fma_f32 v[12:13], v[88:89], v[82:83], v[12:13]
	v_pk_fma_f32 v[14:15], v[90:91], v[86:87], v[14:15]
	v_pk_fma_f32 v[14:15], v[88:89], v[84:85], v[14:15]
	v_add_f32_e32 v6, v12, v13
	v_add_f32_e32 v7, v14, v15
	ds_write2st64_b32 v131, v6, v7 offset0:188 offset1:192
	ds_read_b128 v[44:47], v130 offset:14976
	ds_read_b128 v[48:51], v130 offset:15232
	ds_read_b128 v[52:55], v130 offset:15488
	ds_read_b128 v[56:59], v130 offset:15744
	ds_read_b128 v[60:63], v130 offset:16000
	ds_read_b128 v[64:67], v130 offset:16256
	ds_read_b128 v[68:71], v130 offset:16512
	ds_read_b128 v[72:75], v130 offset:16768
	ds_read_b128 v[76:79], v130 offset:17024
	ds_read_b128 v[80:83], v129 offset:17408
	ds_read_b128 v[84:87], v129 offset:17424
	ds_read_b32 v89, v128 offset:17280
	ds_read_b32 v91, v128 offset:17344
	s_waitcnt lgkmcnt(13)
	v_pk_mul_f32 v[4:5], v[0:1], v[196:197]
	v_pk_mul_f32 v[6:7], v[0:1], v[200:201]
	v_pk_fma_f32 v[4:5], v[2:3], v[198:199], v[4:5]
	v_pk_fma_f32 v[6:7], v[2:3], v[202:203], v[6:7]
	v_add_f32_e32 v22, v4, v5
	v_add_f32_e32 v42, v6, v7
	v_pk_mul_f32 v[8:9], v[0:1], v[204:205]
	v_add_f32_dpp v22, v22, v22 quad_perm:[1,0,3,2] row_mask:0xf bank_mask:0xf bound_ctrl:1
	v_add_f32_dpp v42, v42, v42 quad_perm:[1,0,3,2] row_mask:0xf bank_mask:0xf bound_ctrl:1
	v_pk_mul_f32 v[10:11], v[2:3], v[206:207]
	v_add_f32_dpp v22, v22, v22 quad_perm:[2,3,0,1] row_mask:0xf bank_mask:0xf bound_ctrl:1
	v_add_f32_dpp v42, v42, v42 quad_perm:[2,3,0,1] row_mask:0xf bank_mask:0xf bound_ctrl:1
	v_pk_mul_f32 v[12:13], v[0:1], v[224:225]
	v_add_f32_dpp v22, v22, v22 row_ror:4 row_mask:0xf bank_mask:0xf bound_ctrl:1
	v_add_f32_dpp v42, v42, v42 row_ror:4 row_mask:0xf bank_mask:0xf bound_ctrl:1
	v_pk_mul_f32 v[14:15], v[0:1], v[228:229]
	v_add_f32_dpp v240, v22, v22 row_ror:8 row_mask:0xf bank_mask:0xf bound_ctrl:1
	v_add_f32_dpp v42, v42, v42 row_ror:8 row_mask:0xf bank_mask:0xf bound_ctrl:1
	v_pk_fma_f32 v[8:9], v[240:241], v[212:213], v[8:9] op_sel:[1,0,0] op_sel_hi:[1,1,1]
	v_pk_fma_f32 v[10:11], v[240:241], v[214:215], v[10:11] op_sel:[1,0,0] op_sel_hi:[1,1,1]
	v_fma_f32 v4, v240, v232, v42
	v_pk_fma_f32 v[8:9], v[242:243], v[220:221], v[8:9] op_sel:[1,0,0] op_sel_hi:[1,1,1]
	v_fma_f32 v242, v241, v233, v4
	v_pk_fma_f32 v[10:11], v[242:243], v[222:223], v[10:11] op_sel:[1,0,0] op_sel_hi:[1,1,1]
	v_pk_fma_f32 v[12:13], v[2:3], v[226:227], v[12:13]
	v_pk_fma_f32 v[14:15], v[2:3], v[230:231], v[14:15]
	v_pk_fma_f32 v[0:1], v[240:241], v[208:209], v[8:9] op_sel:[0,0,0] op_sel_hi:[0,1,1]
	v_pk_fma_f32 v[2:3], v[240:241], v[210:211], v[10:11] op_sel:[0,0,0] op_sel_hi:[0,1,1]
	v_pk_fma_f32 v[0:1], v[242:243], v[216:217], v[0:1] op_sel:[0,0,0] op_sel_hi:[0,1,1]
	v_pk_fma_f32 v[2:3], v[242:243], v[218:219], v[2:3] op_sel:[0,0,0] op_sel_hi:[0,1,1]
	v_pk_fma_f32 v[12:13], v[240:241], v[234:235], v[12:13]
	v_pk_fma_f32 v[14:15], v[242:243], v[238:239], v[14:15]
	v_pk_fma_f32 v[14:15], v[240:241], v[236:237], v[14:15]
	v_add_f32_e32 v6, v12, v13
	v_add_f32_e32 v7, v14, v15
	ds_write2st64_b32 v131, v6, v7 offset0:196 offset1:200
	ds_read_b128 v[196:199], v130 offset:17472
	ds_read_b128 v[200:203], v130 offset:17728
	ds_read_b128 v[204:207], v130 offset:17984
	ds_read_b128 v[208:211], v130 offset:18240
	ds_read_b128 v[212:215], v130 offset:18496
	ds_read_b128 v[216:219], v130 offset:18752
	ds_read_b128 v[220:223], v130 offset:19008
	ds_read_b128 v[224:227], v130 offset:19264
	ds_read_b128 v[228:231], v130 offset:19520
	ds_read_b128 v[232:235], v129 offset:19904
	ds_read_b128 v[236:239], v129 offset:19920
	ds_read_b32 v241, v128 offset:19776
	ds_read_b32 v243, v128 offset:19840
	s_waitcnt lgkmcnt(13)
	v_pk_mul_f32 v[4:5], v[0:1], v[44:45]
	v_pk_mul_f32 v[6:7], v[0:1], v[48:49]
	v_pk_fma_f32 v[4:5], v[2:3], v[46:47], v[4:5]
	v_pk_fma_f32 v[6:7], v[2:3], v[50:51], v[6:7]
	v_add_f32_e32 v22, v4, v5
	v_add_f32_e32 v42, v6, v7
	v_pk_mul_f32 v[8:9], v[0:1], v[52:53]
	v_add_f32_dpp v22, v22, v22 quad_perm:[1,0,3,2] row_mask:0xf bank_mask:0xf bound_ctrl:1
	v_add_f32_dpp v42, v42, v42 quad_perm:[1,0,3,2] row_mask:0xf bank_mask:0xf bound_ctrl:1
	v_pk_mul_f32 v[10:11], v[2:3], v[54:55]
	v_add_f32_dpp v22, v22, v22 quad_perm:[2,3,0,1] row_mask:0xf bank_mask:0xf bound_ctrl:1
	v_add_f32_dpp v42, v42, v42 quad_perm:[2,3,0,1] row_mask:0xf bank_mask:0xf bound_ctrl:1
	v_pk_mul_f32 v[12:13], v[0:1], v[72:73]
	v_add_f32_dpp v22, v22, v22 row_ror:4 row_mask:0xf bank_mask:0xf bound_ctrl:1
	v_add_f32_dpp v42, v42, v42 row_ror:4 row_mask:0xf bank_mask:0xf bound_ctrl:1
	v_pk_mul_f32 v[14:15], v[0:1], v[76:77]
	v_add_f32_dpp v88, v22, v22 row_ror:8 row_mask:0xf bank_mask:0xf bound_ctrl:1
	v_add_f32_dpp v42, v42, v42 row_ror:8 row_mask:0xf bank_mask:0xf bound_ctrl:1
	v_pk_fma_f32 v[8:9], v[88:89], v[60:61], v[8:9] op_sel:[1,0,0] op_sel_hi:[1,1,1]
	v_pk_fma_f32 v[10:11], v[88:89], v[62:63], v[10:11] op_sel:[1,0,0] op_sel_hi:[1,1,1]
	v_fma_f32 v4, v88, v80, v42
	v_pk_fma_f32 v[8:9], v[90:91], v[68:69], v[8:9] op_sel:[1,0,0] op_sel_hi:[1,1,1]
	v_fma_f32 v90, v89, v81, v4
	v_pk_fma_f32 v[10:11], v[90:91], v[70:71], v[10:11] op_sel:[1,0,0] op_sel_hi:[1,1,1]
	v_pk_fma_f32 v[12:13], v[2:3], v[74:75], v[12:13]
	v_pk_fma_f32 v[14:15], v[2:3], v[78:79], v[14:15]
	v_pk_fma_f32 v[0:1], v[88:89], v[56:57], v[8:9] op_sel:[0,0,0] op_sel_hi:[0,1,1]
	v_pk_fma_f32 v[2:3], v[88:89], v[58:59], v[10:11] op_sel:[0,0,0] op_sel_hi:[0,1,1]
	v_pk_fma_f32 v[0:1], v[90:91], v[64:65], v[0:1] op_sel:[0,0,0] op_sel_hi:[0,1,1]
	v_pk_fma_f32 v[2:3], v[90:91], v[66:67], v[2:3] op_sel:[0,0,0] op_sel_hi:[0,1,1]
	v_pk_fma_f32 v[12:13], v[88:89], v[82:83], v[12:13]
	v_pk_fma_f32 v[14:15], v[90:91], v[86:87], v[14:15]
	v_pk_fma_f32 v[14:15], v[88:89], v[84:85], v[14:15]
	v_add_f32_e32 v6, v12, v13
	v_add_f32_e32 v7, v14, v15
	ds_write2st64_b32 v131, v6, v7 offset0:204 offset1:208
	s_waitcnt lgkmcnt(0)
	v_pk_mul_f32 v[4:5], v[0:1], v[196:197]
	v_pk_mul_f32 v[6:7], v[0:1], v[200:201]
	v_pk_fma_f32 v[4:5], v[2:3], v[198:199], v[4:5]
	v_pk_fma_f32 v[6:7], v[2:3], v[202:203], v[6:7]
	v_add_f32_e32 v22, v4, v5
	v_add_f32_e32 v42, v6, v7
	v_pk_mul_f32 v[8:9], v[0:1], v[204:205]
	v_add_f32_dpp v22, v22, v22 quad_perm:[1,0,3,2] row_mask:0xf bank_mask:0xf bound_ctrl:1
	v_add_f32_dpp v42, v42, v42 quad_perm:[1,0,3,2] row_mask:0xf bank_mask:0xf bound_ctrl:1
	v_pk_mul_f32 v[10:11], v[2:3], v[206:207]
	v_add_f32_dpp v22, v22, v22 quad_perm:[2,3,0,1] row_mask:0xf bank_mask:0xf bound_ctrl:1
	v_add_f32_dpp v42, v42, v42 quad_perm:[2,3,0,1] row_mask:0xf bank_mask:0xf bound_ctrl:1
	v_pk_mul_f32 v[12:13], v[0:1], v[224:225]
	v_add_f32_dpp v22, v22, v22 row_ror:4 row_mask:0xf bank_mask:0xf bound_ctrl:1
	v_add_f32_dpp v42, v42, v42 row_ror:4 row_mask:0xf bank_mask:0xf bound_ctrl:1
	v_pk_mul_f32 v[14:15], v[0:1], v[228:229]
	v_add_f32_dpp v240, v22, v22 row_ror:8 row_mask:0xf bank_mask:0xf bound_ctrl:1
	v_add_f32_dpp v42, v42, v42 row_ror:8 row_mask:0xf bank_mask:0xf bound_ctrl:1
	v_pk_fma_f32 v[8:9], v[240:241], v[212:213], v[8:9] op_sel:[1,0,0] op_sel_hi:[1,1,1]
	v_pk_fma_f32 v[10:11], v[240:241], v[214:215], v[10:11] op_sel:[1,0,0] op_sel_hi:[1,1,1]
	v_fma_f32 v4, v240, v232, v42
	v_pk_fma_f32 v[8:9], v[242:243], v[220:221], v[8:9] op_sel:[1,0,0] op_sel_hi:[1,1,1]
	v_fma_f32 v242, v241, v233, v4
	v_pk_fma_f32 v[10:11], v[242:243], v[222:223], v[10:11] op_sel:[1,0,0] op_sel_hi:[1,1,1]
	v_pk_fma_f32 v[12:13], v[2:3], v[226:227], v[12:13]
	v_pk_fma_f32 v[14:15], v[2:3], v[230:231], v[14:15]
	v_pk_fma_f32 v[0:1], v[240:241], v[208:209], v[8:9] op_sel:[0,0,0] op_sel_hi:[0,1,1]
	v_pk_fma_f32 v[2:3], v[240:241], v[210:211], v[10:11] op_sel:[0,0,0] op_sel_hi:[0,1,1]
	v_pk_fma_f32 v[0:1], v[242:243], v[216:217], v[0:1] op_sel:[0,0,0] op_sel_hi:[0,1,1]
	v_pk_fma_f32 v[2:3], v[242:243], v[218:219], v[2:3] op_sel:[0,0,0] op_sel_hi:[0,1,1]
	v_pk_fma_f32 v[12:13], v[240:241], v[234:235], v[12:13]
	v_pk_fma_f32 v[14:15], v[242:243], v[238:239], v[14:15]
	v_pk_fma_f32 v[14:15], v[240:241], v[236:237], v[14:15]
	v_add_f32_e32 v6, v12, v13
	v_add_f32_e32 v7, v14, v15
	ds_write2st64_b32 v131, v6, v7 offset0:212 offset1:216
	s_waitcnt lgkmcnt(0)
	s_barrier
	s_cmpk_eq_i32 s10, 0x100
	s_cbranch_scc0 .LBB0_1112
	ds_read_b128 v[4:7], v148 offset:56320
	ds_read_b128 v[8:11], v148 offset:56336
	ds_read_b128 v[12:15], v148 offset:56352
	ds_read_b128 v[44:47], v148 offset:56368
	v_lshlrev_b32_e32 v22, 1, v18
	s_waitcnt lgkmcnt(3)
	v_mov_b32_e32 v48, v5
	v_mov_b32_e32 v49, v6
	s_waitcnt lgkmcnt(2)
	v_mov_b32_e32 v50, v9
	v_mov_b32_e32 v51, v10
	v_mov_b32_e32 v5, v7
	v_mov_b32_e32 v9, v11
	v_pk_add_f32 v[4:5], v[48:49], v[4:5]
	v_pk_add_f32 v[6:7], v[50:51], v[8:9]
	s_waitcnt lgkmcnt(1)
	v_mov_b32_e32 v8, v13
	v_mov_b32_e32 v10, v15
	v_pk_add_f32 v[4:5], v[4:5], v[4:5] op_sel:[0,1] op_sel_hi:[1,0]
	v_pk_add_f32 v[6:7], v[6:7], v[6:7] op_sel:[0,1] op_sel_hi:[1,0]
	v_pk_add_f32 v[8:9], v[12:13], v[8:9]
	v_pk_add_f32 v[10:11], v[14:15], v[10:11]
	s_waitcnt lgkmcnt(0)
	v_mov_b32_e32 v5, v44
	v_mov_b32_e32 v7, v45
	v_mov_b32_e32 v9, v46
	v_mov_b32_e32 v11, v47
	v_pk_add_f32 v[4:5], v[4:5], v[6:7]
	v_pk_add_f32 v[6:7], v[8:9], v[10:11]
	s_lshl_b32 s72, s12, 4
	v_pk_add_f32 v[4:5], v[4:5], v[6:7]
	v_mov_b64_e32 v[6:7], s[88:89]
	v_pk_add_f32 v[4:5], v[4:5], v[4:5] op_sel:[0,1] op_sel_hi:[1,0]
	s_nop 0
	v_bfe_u32 v5, v4, 16, 1
	v_add3_u32 v8, v4, v5, s41
	v_lshl_add_u64 v[4:5], v[24:25], 0, s[94:95]
	v_mad_u64_u32 v[6:7], s[10:11], v4, s40, v[6:7]
	v_mad_i32_i24 v7, v5, s40, v7
	s_lshl_b32 s10, s13, 7
	s_mov_b32 s11, s73
	v_lshl_add_u64 v[4:5], v[6:7], 0, s[10:11]
	s_lshl_b32 s10, s12, 5
	v_lshl_add_u64 v[4:5], v[4:5], 0, s[10:11]
	s_lshl_b32 s10, s16, 4
	s_or_b32 s10, s10, s13
	s_ashr_i32 s11, s10, 31
	v_lshl_add_u64 v[4:5], v[4:5], 0, v[22:23]
	s_lshl_b64 s[10:11], s[10:11], 14
	global_store_short_d16_hi v[4:5], v8, off
	v_lshl_add_u64 v[4:5], s[72:73], 0, v[16:17]
	s_add_u32 s10, s34, s10
	v_lshlrev_b64 v[4:5], 8, v[4:5]
	s_addc_u32 s11, s35, s11
	v_lshl_add_u64 v[4:5], s[10:11], 0, v[4:5]
	v_lshlrev_b32_e32 v22, 2, v20
	v_lshl_add_u64 v[4:5], v[4:5], 0, v[22:23]
	global_store_dwordx4 v[4:5], v[0:3], off

.LBB0_1127:
	s_or_b64 exec, exec, s[10:11]
	v_lshlrev_b64 v[12:13], 1, v[48:49]
	v_lshlrev_b64 v[56:57], 1, v[50:51]
	v_lshl_add_u64 v[48:49], s[28:29], 0, v[12:13]
	v_lshl_add_u64 v[50:51], s[28:29], 0, v[56:57]
	v_lshl_add_u64 v[52:53], s[66:67], 0, v[12:13]
	v_lshl_add_u64 v[58:59], s[66:67], 0, v[56:57]
	global_load_dwordx2 v[88:89], v[48:49], off
	global_load_dwordx2 v[76:77], v[50:51], off
	global_load_dwordx2 v[86:87], v[52:53], off
	s_nop 0
	global_load_dwordx2 v[48:49], v[58:59], off
	v_lshl_add_u64 v[50:51], s[54:55], 0, v[12:13]
	v_lshl_add_u64 v[52:53], s[54:55], 0, v[56:57]
	v_lshl_add_u64 v[58:59], s[62:63], 0, v[12:13]
	v_lshl_add_u64 v[60:61], s[62:63], 0, v[56:57]
	v_lshl_add_u64 v[12:13], s[96:97], 0, v[12:13]
	v_lshl_add_u64 v[56:57], s[96:97], 0, v[56:57]
	v_lshlrev_b64 v[54:55], 1, v[54:55]
	v_lshlrev_b64 v[14:15], 1, v[14:15]
	global_load_dwordx2 v[80:81], v[50:51], off
	s_nop 0
	global_load_dwordx2 v[50:51], v[52:53], off
	global_load_dwordx2 v[78:79], v[58:59], off
	s_nop 0
	global_load_dwordx2 v[52:53], v[60:61], off
	v_lshl_add_u64 v[58:59], s[28:29], 0, v[54:55]
	v_lshl_add_u64 v[60:61], s[28:29], 0, v[14:15]
	global_load_dwordx2 v[82:83], v[12:13], off
	s_nop 0
	global_load_dwordx2 v[56:57], v[56:57], off
	s_nop 0
	global_load_dwordx2 v[96:97], v[58:59], off
	global_load_dwordx2 v[84:85], v[60:61], off
	v_lshl_add_u64 v[12:13], s[66:67], 0, v[54:55]
	v_lshl_add_u64 v[58:59], s[66:67], 0, v[14:15]
	v_lshl_add_u64 v[60:61], s[54:55], 0, v[54:55]
	v_lshl_add_u64 v[62:63], s[54:55], 0, v[14:15]
	global_load_dwordx2 v[98:99], v[12:13], off
	global_load_dwordx2 v[68:69], v[58:59], off
	global_load_dwordx2 v[90:91], v[60:61], off
	global_load_dwordx2 v[64:65], v[62:63], off
	v_lshl_add_u64 v[12:13], s[62:63], 0, v[54:55]
	v_lshl_add_u64 v[58:59], s[62:63], 0, v[14:15]
	v_lshl_add_u64 v[54:55], s[96:97], 0, v[54:55]
	v_lshl_add_u64 v[14:15], s[96:97], 0, v[14:15]
	global_load_dwordx2 v[92:93], v[12:13], off
	global_load_dwordx2 v[72:73], v[58:59], off
	global_load_dwordx2 v[94:95], v[54:55], off
	global_load_dwordx2 v[74:75], v[14:15], off
	s_lshr_b32 s8, s44, 2
	s_and_b32 s8, s8, 15
	s_and_b32 s9, s43, 3
	s_lshl_b32 s45, s8, 7
	s_lshl_b32 s47, s9, 5
	s_lshl_b32 s52, s8, 2
	s_lshl_b32 s8, s38, 1
	s_add_u32 s8, s88, s8
	s_addc_u32 s9, s89, 0
	s_lshl_b32 s10, s12, 5
	s_add_u32 s8, s8, s10
	s_addc_u32 s9, s9, 0
	s_lshl_b32 s10, s13, 2
	s_add_u32 s10, s58, s10
	v_lshlrev_b32_e32 v12, 1, v18
	v_mov_b32_e32 v13, v23
	s_addc_u32 s11, s59, 0
	s_lshl_b64 s[38:39], s[16:17], 23
	v_lshl_or_b32 v22, v20, 1, s45
	s_waitcnt lgkmcnt(0)
	s_barrier
	v_lshl_add_u64 v[54:55], s[8:9], 0, v[12:13]
	v_mov_b32_e32 v13, s39
	v_or_b32_e32 v12, s38, v32
	s_mul_hi_i32 s39, s16, 0x880000
	s_mul_i32 s38, s16, 0x880000
	s_or_b32 s45, s47, s45
	s_lshl_b64 s[16:17], s[16:17], 18
	s_or_b32 s38, s38, s45
	s_or_b32 s16, s16, s52
	v_cmp_eq_u32_e64 s[8:9], 0, v102
	v_cmp_eq_u32_e64 s[12:13], s12, v31
	v_lshl_add_u64 v[58:59], v[12:13], 0, v[22:23]
	v_lshl_add_u64 v[60:61], s[38:39], 0, v[34:35]
	v_lshl_add_u64 v[62:63], s[38:39], 0, v[38:39]
	v_lshl_add_u64 v[66:67], s[16:17], 0, v[40:41]
	s_mov_b32 s72, -1
	v_mov_b64_e32 v[70:71], v[36:37]
	s_mov_b64 s[98:99], exec
	s_andn2_b64 exec, exec, s[6:7]
	s_cbranch_execz .Lh1skipP
	s_waitcnt vmcnt(8)
	v_lshlrev_b32_e32 v13, 16, v52
	v_and_b32_e32 v15, 0xffff0000, v52
	v_lshlrev_b32_e32 v101, 16, v53
	s_waitcnt vmcnt(6)
	v_lshlrev_b32_e32 v100, 16, v49
	v_and_b32_e32 v103, 0xffff0000, v53
	v_and_b32_e32 v102, 0xffff0000, v49
	v_add_f32_e32 v117, -1.0, v102
	v_mov_b32_e32 v116, v103
	v_add_f32_e32 v113, -1.0, v100
	v_mov_b32_e32 v108, v13
	v_mov_b32_e32 v109, v15
	v_mov_b32_e32 v112, v101
	v_pk_mul_f32 v[114:115], v[44:45], v[116:117]
	v_pk_mul_f32 v[118:119], v[0:1], v[108:109]
	v_pk_mul_f32 v[120:121], v[46:47], v[112:113]
	v_pk_mul_f32 v[108:109], v[118:119], v[118:119]
	v_mov_b32_e32 v110, v114
	v_mov_b32_e32 v111, v120
	v_pk_mul_f32 v[110:111], v[110:111], v[110:111]
	v_add_f32_e32 v12, v108, v109
	v_add_f32_e32 v12, v12, v111
	v_add_f32_e32 v12, v110, v12
	s_waitcnt vmcnt(10)
	v_lshlrev_b32_e32 v106, 16, v56
	v_and_b32_e32 v107, 0xffff0000, v56
	v_add_f32_dpp v12, v12, v12 quad_perm:[1,0,3,2] row_mask:0xf bank_mask:0xf bound_ctrl:1
	v_lshlrev_b32_e32 v104, 16, v57
	v_and_b32_e32 v105, 0xffff0000, v57
	v_add_f32_dpp v12, v12, v12 quad_perm:[2,3,0,1] row_mask:0xf bank_mask:0xf bound_ctrl:1
	s_nop 1
	v_add_f32_dpp v12, v12, v12 row_ror:4 row_mask:0xf bank_mask:0xf bound_ctrl:1
	s_nop 1
	v_add_f32_dpp v12, v12, v12 row_ror:8 row_mask:0xf bank_mask:0xf bound_ctrl:1
	v_mul_f32_e32 v14, 0x4f800000, v12
	v_cmp_gt_f32_e32 vcc, s42, v12
	s_nop 1
	v_cndmask_b32_e32 v22, v12, v14, vcc
	v_sqrt_f32_e32 v42, v22
	v_lshlrev_b32_e32 v12, 16, v48
	v_and_b32_e32 v14, 0xffff0000, v48
	v_add_f32_e32 v108, -1.0, v12
	v_add_u32_e32 v109, -1, v42
	v_fma_f32 v110, -v109, v42, v22
	v_cmp_ge_f32_e64 s[16:17], 0, v110
	v_add_u32_e32 v110, 1, v42
	s_nop 0
	v_cndmask_b32_e64 v109, v42, v109, s[16:17]
	v_fma_f32 v42, -v110, v42, v22
	v_cmp_lt_f32_e64 s[16:17], 0, v42
	s_nop 1
	v_cndmask_b32_e64 v42, v109, v110, s[16:17]
	v_mul_f32_e32 v109, 0x37800000, v42
	v_cndmask_b32_e32 v42, v42, v109, vcc
	v_cmp_class_f32_e32 vcc, v22, v149
	v_fma_f32 v109, v4, v108, 1.0
	v_add_f32_e32 v108, -1.0, v14
	v_cndmask_b32_e32 v22, v42, v22, vcc
	v_max_f32_e32 v22, 0x2b8cbccc, v22
	v_div_scale_f32 v42, s[16:17], v22, v22, 1.0
	v_rcp_f32_e32 v110, v42
	v_fma_f32 v111, v5, v108, 1.0
	v_fma_f32 v108, -v42, v110, 1.0
	v_fmac_f32_e32 v110, v108, v110
	v_div_scale_f32 v108, vcc, 1.0, v22, 1.0
	v_mul_f32_e32 v122, v108, v110
	v_fma_f32 v123, -v42, v122, v108
	v_fmac_f32_e32 v122, v123, v110
	v_fma_f32 v42, -v42, v122, v108
	v_div_fmas_f32 v42, v42, v110, v122
	v_div_fixup_f32 v42, v42, v22, 1.0
	v_mul_f32_e32 v108, v118, v42
	v_mul_f32_e32 v110, v119, v42
	v_pk_mul_f32 v[108:109], v[108:109], v[12:13]
	v_pk_mul_f32 v[110:111], v[110:111], v[14:15]
	v_pk_mul_f32 v[12:13], v[120:121], v[42:43]
	v_pk_fma_f32 v[14:15], v[46:47], v[112:113], s[2:3]
	v_pk_mul_f32 v[122:123], v[108:109], v[106:107] op_sel:[1,0] op_sel_hi:[0,1]
	v_mov_b32_e32 v13, v15
	v_pk_mul_f32 v[112:113], v[12:13], v[100:101]
	v_pk_mul_f32 v[12:13], v[114:115], v[42:43]
	v_pk_fma_f32 v[14:15], v[44:45], v[116:117], s[2:3]
	v_fma_f32 v22, v8, v122, 0
	v_pk_mul_f32 v[124:125], v[110:111], v[106:107]
	v_mov_b32_e32 v13, v15
	v_fmac_f32_e32 v22, v9, v125
	v_pk_mul_f32 v[130:131], v[112:113], v[104:105] op_sel:[1,0] op_sel_hi:[0,1]
	v_pk_mul_f32 v[116:117], v[12:13], v[102:103]
	v_fmac_f32_e32 v22, v10, v130
	v_pk_mul_f32 v[132:133], v[116:117], v[104:105]
	s_nop 0
	v_fmac_f32_e32 v22, v11, v133
	s_nop 1
	v_add_f32_dpp v12, v22, v22 quad_perm:[1,0,3,2] row_mask:0xf bank_mask:0xf bound_ctrl:1
	s_nop 1
	v_add_f32_dpp v12, v12, v12 quad_perm:[2,3,0,1] row_mask:0xf bank_mask:0xf bound_ctrl:1
	s_nop 1
	v_add_f32_dpp v12, v12, v12 row_ror:4 row_mask:0xf bank_mask:0xf bound_ctrl:1
	s_nop 1
	v_mov_b32_dpp v13, v12 row_ror:8 row_mask:0xf bank_mask:0xf bound_ctrl:1
.Lh1skipP:
	s_mov_b64 exec, s[98:99]
	s_branch .LBB0_1129
.LBB0_1128:
	s_or_b64 exec, exec, s[38:39]
	s_mov_b64 s[98:99], exec
	s_andn2_b64 exec, exec, s[6:7]
	s_cbranch_execz .Lh1skip0
	s_waitcnt vmcnt(8)
	v_lshlrev_b32_e32 v13, 16, v52
	v_and_b32_e32 v15, 0xffff0000, v52
	v_lshlrev_b32_e32 v101, 16, v53
	s_waitcnt vmcnt(6)
	v_lshlrev_b32_e32 v100, 16, v49
	v_and_b32_e32 v103, 0xffff0000, v53
	v_and_b32_e32 v102, 0xffff0000, v49
	v_add_f32_e32 v117, -1.0, v102
	v_mov_b32_e32 v116, v103
	v_add_f32_e32 v113, -1.0, v100
	v_mov_b32_e32 v108, v13
	v_mov_b32_e32 v109, v15
	v_mov_b32_e32 v112, v101
	v_pk_mul_f32 v[114:115], v[44:45], v[116:117]
	v_pk_mul_f32 v[118:119], v[0:1], v[108:109]
	v_pk_mul_f32 v[120:121], v[46:47], v[112:113]
	v_pk_mul_f32 v[108:109], v[118:119], v[118:119]
	v_mov_b32_e32 v110, v114
	v_mov_b32_e32 v111, v120
	v_pk_mul_f32 v[110:111], v[110:111], v[110:111]
	v_add_f32_e32 v12, v108, v109
	v_add_f32_e32 v12, v12, v111
	v_add_f32_e32 v12, v110, v12
	s_waitcnt vmcnt(10)
	v_lshlrev_b32_e32 v106, 16, v56
	v_and_b32_e32 v107, 0xffff0000, v56
	v_add_f32_dpp v12, v12, v12 quad_perm:[1,0,3,2] row_mask:0xf bank_mask:0xf bound_ctrl:1
	v_lshlrev_b32_e32 v104, 16, v57
	v_and_b32_e32 v105, 0xffff0000, v57
	v_add_f32_dpp v12, v12, v12 quad_perm:[2,3,0,1] row_mask:0xf bank_mask:0xf bound_ctrl:1
	s_nop 1
	v_add_f32_dpp v12, v12, v12 row_ror:4 row_mask:0xf bank_mask:0xf bound_ctrl:1
	s_nop 1
	v_add_f32_dpp v12, v12, v12 row_ror:8 row_mask:0xf bank_mask:0xf bound_ctrl:1
	v_mul_f32_e32 v14, 0x4f800000, v12
	v_cmp_gt_f32_e32 vcc, s42, v12
	s_nop 1
	v_cndmask_b32_e32 v22, v12, v14, vcc
	v_sqrt_f32_e32 v42, v22
	v_lshlrev_b32_e32 v12, 16, v48
	v_and_b32_e32 v14, 0xffff0000, v48
	v_add_f32_e32 v108, -1.0, v12
	v_add_u32_e32 v109, -1, v42
	v_fma_f32 v110, -v109, v42, v22
	v_cmp_ge_f32_e64 s[16:17], 0, v110
	v_add_u32_e32 v110, 1, v42
	s_nop 0
	v_cndmask_b32_e64 v109, v42, v109, s[16:17]
	v_fma_f32 v42, -v110, v42, v22
	v_cmp_lt_f32_e64 s[16:17], 0, v42
	s_nop 1
	v_cndmask_b32_e64 v42, v109, v110, s[16:17]
	v_mul_f32_e32 v109, 0x37800000, v42
	v_cndmask_b32_e32 v42, v42, v109, vcc
	v_cmp_class_f32_e32 vcc, v22, v149
	v_fma_f32 v109, v4, v108, 1.0
	v_add_f32_e32 v108, -1.0, v14
	v_cndmask_b32_e32 v22, v42, v22, vcc
	v_max_f32_e32 v22, 0x2b8cbccc, v22
	v_div_scale_f32 v42, s[16:17], v22, v22, 1.0
	v_rcp_f32_e32 v110, v42
	v_fma_f32 v111, v5, v108, 1.0
	v_fma_f32 v108, -v42, v110, 1.0
	v_fmac_f32_e32 v110, v108, v110
	v_div_scale_f32 v108, vcc, 1.0, v22, 1.0
	v_mul_f32_e32 v122, v108, v110
	v_fma_f32 v123, -v42, v122, v108
	v_fmac_f32_e32 v122, v123, v110
	v_fma_f32 v42, -v42, v122, v108
	v_div_fmas_f32 v42, v42, v110, v122
	v_div_fixup_f32 v42, v42, v22, 1.0
	v_mul_f32_e32 v108, v118, v42
	v_mul_f32_e32 v110, v119, v42
	v_pk_mul_f32 v[108:109], v[108:109], v[12:13]
	v_pk_mul_f32 v[110:111], v[110:111], v[14:15]
	v_pk_mul_f32 v[12:13], v[120:121], v[42:43]
	v_pk_fma_f32 v[14:15], v[46:47], v[112:113], s[2:3]
	v_pk_mul_f32 v[122:123], v[108:109], v[106:107] op_sel:[1,0] op_sel_hi:[0,1]
	v_mov_b32_e32 v13, v15
	v_pk_mul_f32 v[112:113], v[12:13], v[100:101]
	v_pk_mul_f32 v[12:13], v[114:115], v[42:43]
	v_pk_fma_f32 v[14:15], v[44:45], v[116:117], s[2:3]
	v_fma_f32 v22, v8, v122, 0
	v_pk_mul_f32 v[124:125], v[110:111], v[106:107]
	v_mov_b32_e32 v13, v15
	v_fmac_f32_e32 v22, v9, v125
	v_pk_mul_f32 v[130:131], v[112:113], v[104:105] op_sel:[1,0] op_sel_hi:[0,1]
	v_pk_mul_f32 v[116:117], v[12:13], v[102:103]
	v_fmac_f32_e32 v22, v10, v130
	v_pk_mul_f32 v[132:133], v[116:117], v[104:105]
	s_nop 0
	v_fmac_f32_e32 v22, v11, v133
	s_nop 1
	v_add_f32_dpp v12, v22, v22 quad_perm:[1,0,3,2] row_mask:0xf bank_mask:0xf bound_ctrl:1
	s_nop 1
	v_add_f32_dpp v12, v12, v12 quad_perm:[2,3,0,1] row_mask:0xf bank_mask:0xf bound_ctrl:1
	s_nop 1
	v_add_f32_dpp v12, v12, v12 row_ror:4 row_mask:0xf bank_mask:0xf bound_ctrl:1
	s_nop 1
	v_mov_b32_dpp v13, v12 row_ror:8 row_mask:0xf bank_mask:0xf bound_ctrl:1
.Lh1skip0:
	s_mov_b64 exec, s[98:99]
	s_waitcnt lgkmcnt(0)
	s_barrier
	s_mov_b64 s[16:17], 0x20000
	s_add_i32 s72, s72, 4
	v_lshl_add_u64 v[58:59], v[58:59], 0, s[16:17]
	s_mov_b64 s[16:17], 0x1000
	v_lshl_add_u64 v[60:61], v[60:61], 0, s[90:91]
	v_lshl_add_u64 v[70:71], v[70:71], 0, 64
	v_lshl_add_u64 v[62:63], v[62:63], 0, s[90:91]
	s_cmpk_gt_u32 s45, 0xfb
	v_lshl_add_u64 v[66:67], v[66:67], 0, s[16:17]
	s_cbranch_scc1 .LBB0_1109

.LBB0_1132:
	s_or_saveexec_b64 s[38:39], s[16:17]
	s_add_i32 s45, s72, 1
	s_xor_b64 exec, exec, s[38:39]
	s_cbranch_execz .LBB0_1141
	s_and_saveexec_b64 s[16:17], s[8:9]
	s_cbranch_execz .LBB0_1135
	v_lshl_add_u64 v[14:15], s[84:85], 0, v[66:67]
	v_add_f32_e32 v12, v12, v13
	global_store_dword v[14:15], v12, off offset:-2048

.LBB0_1141:
	s_or_b64 exec, exec, s[38:39]
	s_mov_b64 s[98:99], exec
	s_andn2_b64 exec, exec, s[14:15]
	s_cbranch_execz .Lh1skip1
	s_waitcnt vmcnt(2)
	v_lshlrev_b32_e32 v13, 16, v72
	v_and_b32_e32 v15, 0xffff0000, v72
	v_lshlrev_b32_e32 v105, 16, v73
	v_lshlrev_b32_e32 v104, 16, v69
	v_and_b32_e32 v107, 0xffff0000, v73
	v_and_b32_e32 v106, 0xffff0000, v69
	v_add_f32_e32 v121, -1.0, v106
	v_mov_b32_e32 v120, v107
	v_add_f32_e32 v117, -1.0, v104
	v_mov_b32_e32 v112, v13
	v_mov_b32_e32 v113, v15
	v_mov_b32_e32 v116, v105
	v_pk_mul_f32 v[118:119], v[44:45], v[120:121]
	v_pk_mul_f32 v[122:123], v[0:1], v[112:113]
	v_pk_mul_f32 v[124:125], v[46:47], v[116:117]
	v_pk_mul_f32 v[112:113], v[122:123], v[122:123]
	v_mov_b32_e32 v114, v118
	v_mov_b32_e32 v115, v124
	v_pk_mul_f32 v[114:115], v[114:115], v[114:115]
	v_add_f32_e32 v12, v112, v113
	v_add_f32_e32 v12, v12, v115
	v_add_f32_e32 v12, v114, v12
	s_waitcnt vmcnt(0)
	v_lshlrev_b32_e32 v110, 16, v74
	v_and_b32_e32 v111, 0xffff0000, v74
	v_add_f32_dpp v12, v12, v12 quad_perm:[1,0,3,2] row_mask:0xf bank_mask:0xf bound_ctrl:1
	v_lshlrev_b32_e32 v108, 16, v75
	v_and_b32_e32 v109, 0xffff0000, v75
	v_add_f32_dpp v12, v12, v12 quad_perm:[2,3,0,1] row_mask:0xf bank_mask:0xf bound_ctrl:1
	s_nop 1
	v_add_f32_dpp v12, v12, v12 row_ror:4 row_mask:0xf bank_mask:0xf bound_ctrl:1
	s_nop 1
	v_add_f32_dpp v12, v12, v12 row_ror:8 row_mask:0xf bank_mask:0xf bound_ctrl:1
	v_mul_f32_e32 v14, 0x4f800000, v12
	v_cmp_gt_f32_e32 vcc, s42, v12
	s_nop 1
	v_cndmask_b32_e32 v22, v12, v14, vcc
	v_sqrt_f32_e32 v42, v22
	v_lshlrev_b32_e32 v12, 16, v68
	v_and_b32_e32 v14, 0xffff0000, v68
	v_add_f32_e32 v112, -1.0, v12
	v_add_u32_e32 v113, -1, v42
	v_fma_f32 v114, -v113, v42, v22
	v_cmp_ge_f32_e64 s[16:17], 0, v114
	v_add_u32_e32 v114, 1, v42
	s_nop 0
	v_cndmask_b32_e64 v113, v42, v113, s[16:17]
	v_fma_f32 v42, -v114, v42, v22
	v_cmp_lt_f32_e64 s[16:17], 0, v42
	s_nop 1
	v_cndmask_b32_e64 v42, v113, v114, s[16:17]
	v_mul_f32_e32 v113, 0x37800000, v42
	v_cndmask_b32_e32 v42, v42, v113, vcc
	v_cmp_class_f32_e32 vcc, v22, v149
	v_fma_f32 v113, v4, v112, 1.0
	v_add_f32_e32 v112, -1.0, v14
	v_cndmask_b32_e32 v22, v42, v22, vcc
	v_max_f32_e32 v22, 0x2b8cbccc, v22
	v_div_scale_f32 v42, s[16:17], v22, v22, 1.0
	v_rcp_f32_e32 v114, v42
	v_fma_f32 v115, v5, v112, 1.0
	v_fma_f32 v112, -v42, v114, 1.0
	v_fmac_f32_e32 v114, v112, v114
	v_div_scale_f32 v112, vcc, 1.0, v22, 1.0
	v_mul_f32_e32 v126, v112, v114
	v_fma_f32 v127, -v42, v126, v112
	v_fmac_f32_e32 v126, v127, v114
	v_fma_f32 v42, -v42, v126, v112
	v_div_fmas_f32 v42, v42, v114, v126
	v_div_fixup_f32 v42, v42, v22, 1.0
	v_mul_f32_e32 v112, v122, v42
	v_mul_f32_e32 v114, v123, v42
	v_pk_mul_f32 v[112:113], v[112:113], v[12:13]
	v_pk_mul_f32 v[114:115], v[114:115], v[14:15]
	v_pk_mul_f32 v[12:13], v[124:125], v[42:43]
	v_pk_fma_f32 v[14:15], v[46:47], v[116:117], s[2:3]
	v_pk_mul_f32 v[126:127], v[112:113], v[110:111] op_sel:[1,0] op_sel_hi:[0,1]
	v_mov_b32_e32 v13, v15
	v_pk_mul_f32 v[116:117], v[12:13], v[104:105]
	v_pk_mul_f32 v[12:13], v[118:119], v[42:43]
	v_pk_fma_f32 v[14:15], v[44:45], v[120:121], s[2:3]
	v_fma_f32 v22, v8, v126, 0
	v_pk_mul_f32 v[128:129], v[114:115], v[110:111]
	v_mov_b32_e32 v13, v15
	v_fmac_f32_e32 v22, v9, v129
	v_pk_mul_f32 v[134:135], v[116:117], v[108:109] op_sel:[1,0] op_sel_hi:[0,1]
	v_pk_mul_f32 v[120:121], v[12:13], v[106:107]
	v_fmac_f32_e32 v22, v10, v134
	v_pk_mul_f32 v[136:137], v[120:121], v[108:109]
	s_nop 0
	v_fmac_f32_e32 v22, v11, v137
	s_nop 1
	v_add_f32_dpp v12, v22, v22 quad_perm:[1,0,3,2] row_mask:0xf bank_mask:0xf bound_ctrl:1
	s_nop 1
	v_add_f32_dpp v12, v12, v12 quad_perm:[2,3,0,1] row_mask:0xf bank_mask:0xf bound_ctrl:1
	s_nop 1
	v_add_f32_dpp v12, v12, v12 row_ror:4 row_mask:0xf bank_mask:0xf bound_ctrl:1
	s_nop 1
	v_mov_b32_dpp v13, v12 row_ror:8 row_mask:0xf bank_mask:0xf bound_ctrl:1
.Lh1skip1:
	s_mov_b64 exec, s[98:99]
	s_waitcnt lgkmcnt(0)
	s_barrier
	v_lshl_add_u64 v[102:103], s[84:85], 0, v[60:61]
	v_lshl_add_u64 v[100:101], s[84:85], 0, v[62:63]
	s_and_saveexec_b64 s[16:17], s[14:15]
	s_xor_b64 s[16:17], exec, s[16:17]
	s_cbranch_execz .LBB0_1143
	ds_read_b128 v[12:15], v146 offset:39936
	ds_read_b128 v[104:107], v146 offset:39952
	ds_read_b128 v[108:111], v146 offset:39968
	ds_read_b128 v[112:115], v146 offset:39984
	s_mov_b32 s38, 0x3018000
	s_waitcnt lgkmcnt(3)
	v_add_f32_e32 v12, v12, v13
	v_add_f32_e32 v13, v14, v15
	v_add_f32_e32 v12, v12, v13
	s_waitcnt lgkmcnt(2)
	v_add_f32_e32 v13, v104, v105
	v_add_f32_e32 v14, v106, v107
	v_add_f32_e32 v13, v13, v14
	v_add_f32_e32 v12, v12, v13
	s_waitcnt lgkmcnt(1)
	v_add_f32_e32 v13, v108, v109
	v_add_f32_e32 v14, v110, v111
	v_add_f32_e32 v13, v13, v14
	v_add_f32_e32 v12, v12, v13
	s_waitcnt lgkmcnt(0)
	v_add_f32_e32 v13, v112, v113
	v_add_f32_e32 v14, v114, v115
	v_add_f32_e32 v13, v13, v14
	v_add_f32_e32 v12, v12, v13
	v_bfe_u32 v13, v12, 16, 1
	v_add3_u32 v22, v12, v13, s41
	v_add_co_u32_e32 v104, vcc, s38, v102
	ds_read_b128 v[12:15], v147 offset:39936
	s_nop 0
	v_addc_co_u32_e32 v105, vcc, 0, v103, vcc
	global_store_short_d16_hi v[104:105], v22, off
	ds_read_b128 v[104:107], v147 offset:39952
	ds_read_b128 v[108:111], v147 offset:39968
	ds_read_b128 v[112:115], v147 offset:39984
	s_waitcnt lgkmcnt(3)
	v_add_f32_e32 v12, v12, v13
	v_add_f32_e32 v13, v14, v15
	v_add_f32_e32 v12, v12, v13
	s_waitcnt lgkmcnt(2)
	v_add_f32_e32 v13, v104, v105
	v_add_f32_e32 v14, v106, v107
	v_add_f32_e32 v13, v13, v14
	v_add_f32_e32 v12, v12, v13
	s_waitcnt lgkmcnt(1)
	v_add_f32_e32 v13, v108, v109
	v_add_f32_e32 v14, v110, v111
	v_add_f32_e32 v13, v13, v14
	v_add_f32_e32 v12, v12, v13
	s_waitcnt lgkmcnt(0)
	v_add_f32_e32 v13, v112, v113
	v_add_f32_e32 v14, v114, v115
	v_add_f32_e32 v13, v13, v14
	v_add_f32_e32 v12, v12, v13
	v_bfe_u32 v13, v12, 16, 1
	v_add3_u32 v14, v12, v13, s41
	v_add_co_u32_e32 v12, vcc, 0x3018000, v100
	s_nop 1
	v_addc_co_u32_e32 v13, vcc, 0, v101, vcc
	global_store_short_d16_hi v[12:13], v14, off
.LBB0_1143:
	s_andn2_saveexec_b64 s[38:39], s[16:17]
	s_cbranch_execz .LBB0_1152
	s_and_saveexec_b64 s[16:17], s[8:9]
	s_cbranch_execz .LBB0_1146
	v_lshl_add_u64 v[14:15], s[84:85], 0, v[66:67]
	v_add_f32_e32 v12, v12, v13
	global_store_dword v[14:15], v12, off offset:-1024

.LBB0_1152:
	s_or_b64 exec, exec, s[38:39]
	s_mov_b64 s[98:99], exec
	s_andn2_b64 exec, exec, s[6:7]
	s_cbranch_execz .Lh1skip2
	s_waitcnt vmcnt(2)
	v_lshlrev_b32_e32 v13, 16, v72
	v_and_b32_e32 v15, 0xffff0000, v72
	v_lshlrev_b32_e32 v105, 16, v73
	v_lshlrev_b32_e32 v104, 16, v69
	v_and_b32_e32 v107, 0xffff0000, v73
	v_and_b32_e32 v106, 0xffff0000, v69
	v_add_f32_e32 v121, -1.0, v106
	v_mov_b32_e32 v120, v107
	v_add_f32_e32 v117, -1.0, v104
	v_mov_b32_e32 v112, v13
	v_mov_b32_e32 v113, v15
	v_mov_b32_e32 v116, v105
	v_pk_mul_f32 v[118:119], v[44:45], v[120:121]
	v_pk_mul_f32 v[122:123], v[0:1], v[112:113]
	v_pk_mul_f32 v[124:125], v[46:47], v[116:117]
	v_pk_mul_f32 v[112:113], v[122:123], v[122:123]
	v_mov_b32_e32 v114, v118
	v_mov_b32_e32 v115, v124
	v_pk_mul_f32 v[114:115], v[114:115], v[114:115]
	v_add_f32_e32 v12, v112, v113
	v_add_f32_e32 v12, v12, v115
	v_add_f32_e32 v12, v114, v12
	s_waitcnt vmcnt(0)
	v_lshlrev_b32_e32 v110, 16, v74
	v_and_b32_e32 v111, 0xffff0000, v74
	v_add_f32_dpp v12, v12, v12 quad_perm:[1,0,3,2] row_mask:0xf bank_mask:0xf bound_ctrl:1
	v_lshlrev_b32_e32 v108, 16, v75
	v_and_b32_e32 v109, 0xffff0000, v75
	v_add_f32_dpp v12, v12, v12 quad_perm:[2,3,0,1] row_mask:0xf bank_mask:0xf bound_ctrl:1
	s_nop 1
	v_add_f32_dpp v12, v12, v12 row_ror:4 row_mask:0xf bank_mask:0xf bound_ctrl:1
	s_nop 1
	v_add_f32_dpp v12, v12, v12 row_ror:8 row_mask:0xf bank_mask:0xf bound_ctrl:1
	v_mul_f32_e32 v14, 0x4f800000, v12
	v_cmp_gt_f32_e32 vcc, s42, v12
	s_nop 1
	v_cndmask_b32_e32 v22, v12, v14, vcc
	v_sqrt_f32_e32 v42, v22
	v_lshlrev_b32_e32 v12, 16, v68
	v_and_b32_e32 v14, 0xffff0000, v68
	v_add_f32_e32 v112, -1.0, v12
	v_add_u32_e32 v113, -1, v42
	v_fma_f32 v114, -v113, v42, v22
	v_cmp_ge_f32_e64 s[16:17], 0, v114
	v_add_u32_e32 v114, 1, v42
	s_nop 0
	v_cndmask_b32_e64 v113, v42, v113, s[16:17]
	v_fma_f32 v42, -v114, v42, v22
	v_cmp_lt_f32_e64 s[16:17], 0, v42
	s_nop 1
	v_cndmask_b32_e64 v42, v113, v114, s[16:17]
	v_mul_f32_e32 v113, 0x37800000, v42
	v_cndmask_b32_e32 v42, v42, v113, vcc
	v_cmp_class_f32_e32 vcc, v22, v149
	v_fma_f32 v113, v4, v112, 1.0
	v_add_f32_e32 v112, -1.0, v14
	v_cndmask_b32_e32 v22, v42, v22, vcc
	v_max_f32_e32 v22, 0x2b8cbccc, v22
	v_div_scale_f32 v42, s[16:17], v22, v22, 1.0
	v_rcp_f32_e32 v114, v42
	v_fma_f32 v115, v5, v112, 1.0
	v_fma_f32 v112, -v42, v114, 1.0
	v_fmac_f32_e32 v114, v112, v114
	v_div_scale_f32 v112, vcc, 1.0, v22, 1.0
	v_mul_f32_e32 v126, v112, v114
	v_fma_f32 v127, -v42, v126, v112
	v_fmac_f32_e32 v126, v127, v114
	v_fma_f32 v42, -v42, v126, v112
	v_div_fmas_f32 v42, v42, v114, v126
	v_div_fixup_f32 v42, v42, v22, 1.0
	v_mul_f32_e32 v112, v122, v42
	v_mul_f32_e32 v114, v123, v42
	v_pk_mul_f32 v[112:113], v[112:113], v[12:13]
	v_pk_mul_f32 v[114:115], v[114:115], v[14:15]
	v_pk_mul_f32 v[12:13], v[124:125], v[42:43]
	v_pk_fma_f32 v[14:15], v[46:47], v[116:117], s[2:3]
	v_pk_mul_f32 v[126:127], v[112:113], v[110:111] op_sel:[1,0] op_sel_hi:[0,1]
	v_mov_b32_e32 v13, v15
	v_pk_mul_f32 v[116:117], v[12:13], v[104:105]
	v_pk_mul_f32 v[12:13], v[118:119], v[42:43]
	v_pk_fma_f32 v[14:15], v[44:45], v[120:121], s[2:3]
	v_fma_f32 v22, v8, v126, 0
	v_pk_mul_f32 v[128:129], v[114:115], v[110:111]
	v_mov_b32_e32 v13, v15
	v_fmac_f32_e32 v22, v9, v129
	v_pk_mul_f32 v[134:135], v[116:117], v[108:109] op_sel:[1,0] op_sel_hi:[0,1]
	v_pk_mul_f32 v[120:121], v[12:13], v[106:107]
	v_fmac_f32_e32 v22, v10, v134
	v_pk_mul_f32 v[136:137], v[120:121], v[108:109]
	s_nop 0
	v_fmac_f32_e32 v22, v11, v137
	s_nop 1
	v_add_f32_dpp v12, v22, v22 quad_perm:[1,0,3,2] row_mask:0xf bank_mask:0xf bound_ctrl:1
	s_nop 1
	v_add_f32_dpp v12, v12, v12 quad_perm:[2,3,0,1] row_mask:0xf bank_mask:0xf bound_ctrl:1
	s_nop 1
	v_add_f32_dpp v12, v12, v12 row_ror:4 row_mask:0xf bank_mask:0xf bound_ctrl:1
	s_nop 1
	v_mov_b32_dpp v13, v12 row_ror:8 row_mask:0xf bank_mask:0xf bound_ctrl:1
.Lh1skip2:
	s_mov_b64 exec, s[98:99]
	s_waitcnt lgkmcnt(0)
	s_barrier
	s_and_saveexec_b64 s[16:17], s[6:7]
	s_xor_b64 s[16:17], exec, s[16:17]
	s_cbranch_execz .LBB0_1154
	ds_read_b128 v[12:15], v146 offset:56320
	ds_read_b128 v[104:107], v146 offset:56336
	ds_read_b128 v[108:111], v146 offset:56352
	ds_read_b128 v[112:115], v146 offset:56368
	s_mov_b32 s38, 0x3020000
	s_waitcnt lgkmcnt(3)
	v_add_f32_e32 v12, v12, v13
	v_add_f32_e32 v13, v14, v15
	v_add_f32_e32 v12, v12, v13
	s_waitcnt lgkmcnt(2)
	v_add_f32_e32 v13, v104, v105
	v_add_f32_e32 v14, v106, v107
	v_add_f32_e32 v13, v13, v14
	v_add_f32_e32 v12, v12, v13
	s_waitcnt lgkmcnt(1)
	v_add_f32_e32 v13, v108, v109
	v_add_f32_e32 v14, v110, v111
	v_add_f32_e32 v13, v13, v14
	v_add_f32_e32 v12, v12, v13
	s_waitcnt lgkmcnt(0)
	v_add_f32_e32 v13, v112, v113
	v_add_f32_e32 v14, v114, v115
	v_add_f32_e32 v13, v13, v14
	v_add_f32_e32 v12, v12, v13
	v_bfe_u32 v13, v12, 16, 1
	v_add3_u32 v22, v12, v13, s41
	v_add_co_u32_e32 v104, vcc, s38, v102
	ds_read_b128 v[12:15], v147 offset:56320
	s_nop 0
	v_addc_co_u32_e32 v105, vcc, 0, v103, vcc
	global_store_short_d16_hi v[104:105], v22, off offset:2048
	ds_read_b128 v[104:107], v147 offset:56336
	ds_read_b128 v[108:111], v147 offset:56352
	ds_read_b128 v[112:115], v147 offset:56368
	s_waitcnt lgkmcnt(3)
	v_add_f32_e32 v12, v12, v13
	v_add_f32_e32 v13, v14, v15
	v_add_f32_e32 v12, v12, v13
	s_waitcnt lgkmcnt(2)
	v_add_f32_e32 v13, v104, v105
	v_add_f32_e32 v14, v106, v107
	v_add_f32_e32 v13, v13, v14
	v_add_f32_e32 v12, v12, v13
	s_waitcnt lgkmcnt(1)
	v_add_f32_e32 v13, v108, v109
	v_add_f32_e32 v14, v110, v111
	v_add_f32_e32 v13, v13, v14
	v_add_f32_e32 v12, v12, v13
	s_waitcnt lgkmcnt(0)
	v_add_f32_e32 v13, v112, v113
	v_add_f32_e32 v14, v114, v115
	v_add_f32_e32 v13, v13, v14
	v_add_f32_e32 v12, v12, v13
	v_bfe_u32 v13, v12, 16, 1
	v_add3_u32 v14, v12, v13, s41
	v_add_co_u32_e32 v12, vcc, 0x3020000, v100
	s_nop 1
	v_addc_co_u32_e32 v13, vcc, 0, v101, vcc
	global_store_short_d16_hi v[12:13], v14, off offset:2048
.LBB0_1154:
	s_andn2_saveexec_b64 s[38:39], s[16:17]
	s_cbranch_execz .LBB0_1163
	s_and_saveexec_b64 s[16:17], s[8:9]
	s_cbranch_execz .LBB0_1157
	v_lshl_add_u64 v[14:15], s[84:85], 0, v[66:67]
	v_add_f32_e32 v12, v12, v13
	global_store_dword v[14:15], v12, off

.LBB0_1163:
	s_or_b64 exec, exec, s[38:39]
	s_mov_b64 s[98:99], exec
	s_andn2_b64 exec, exec, s[14:15]
	s_cbranch_execz .Lh1skip3
	s_waitcnt vmcnt(8)
	v_lshlrev_b32_e32 v13, 16, v52
	v_and_b32_e32 v15, 0xffff0000, v52
	v_lshlrev_b32_e32 v101, 16, v53
	s_waitcnt vmcnt(6)
	v_lshlrev_b32_e32 v100, 16, v49
	v_and_b32_e32 v103, 0xffff0000, v53
	v_and_b32_e32 v102, 0xffff0000, v49
	v_add_f32_e32 v117, -1.0, v102
	v_mov_b32_e32 v116, v103
	v_add_f32_e32 v113, -1.0, v100
	v_mov_b32_e32 v108, v13
	v_mov_b32_e32 v109, v15
	v_mov_b32_e32 v112, v101
	v_pk_mul_f32 v[114:115], v[44:45], v[116:117]
	v_pk_mul_f32 v[118:119], v[0:1], v[108:109]
	v_pk_mul_f32 v[120:121], v[46:47], v[112:113]
	v_pk_mul_f32 v[108:109], v[118:119], v[118:119]
	v_mov_b32_e32 v110, v114
	v_mov_b32_e32 v111, v120
	v_pk_mul_f32 v[110:111], v[110:111], v[110:111]
	v_add_f32_e32 v12, v108, v109
	v_add_f32_e32 v12, v12, v111
	v_add_f32_e32 v12, v110, v12
	v_lshlrev_b32_e32 v106, 16, v56
	v_and_b32_e32 v107, 0xffff0000, v56
	v_add_f32_dpp v12, v12, v12 quad_perm:[1,0,3,2] row_mask:0xf bank_mask:0xf bound_ctrl:1
	v_lshlrev_b32_e32 v104, 16, v57
	v_and_b32_e32 v105, 0xffff0000, v57
	v_add_f32_dpp v12, v12, v12 quad_perm:[2,3,0,1] row_mask:0xf bank_mask:0xf bound_ctrl:1
	v_lshl_add_u64 v[142:143], s[84:85], 0, v[66:67]
	s_nop 0
	v_add_f32_dpp v12, v12, v12 row_ror:4 row_mask:0xf bank_mask:0xf bound_ctrl:1
	s_nop 1
	v_add_f32_dpp v12, v12, v12 row_ror:8 row_mask:0xf bank_mask:0xf bound_ctrl:1
	v_mul_f32_e32 v14, 0x4f800000, v12
	v_cmp_gt_f32_e32 vcc, s42, v12
	s_nop 1
	v_cndmask_b32_e32 v22, v12, v14, vcc
	v_sqrt_f32_e32 v42, v22
	v_lshlrev_b32_e32 v12, 16, v48
	v_and_b32_e32 v14, 0xffff0000, v48
	v_add_f32_e32 v108, -1.0, v12
	v_add_u32_e32 v109, -1, v42
	v_fma_f32 v110, -v109, v42, v22
	v_cmp_ge_f32_e64 s[16:17], 0, v110
	v_add_u32_e32 v110, 1, v42
	s_nop 0
	v_cndmask_b32_e64 v109, v42, v109, s[16:17]
	v_fma_f32 v42, -v110, v42, v22
	v_cmp_lt_f32_e64 s[16:17], 0, v42
	s_nop 1
	v_cndmask_b32_e64 v42, v109, v110, s[16:17]
	v_mul_f32_e32 v109, 0x37800000, v42
	v_cndmask_b32_e32 v42, v42, v109, vcc
	v_cmp_class_f32_e32 vcc, v22, v149
	v_fma_f32 v109, v4, v108, 1.0
	v_add_f32_e32 v108, -1.0, v14
	v_cndmask_b32_e32 v22, v42, v22, vcc
	v_max_f32_e32 v22, 0x2b8cbccc, v22
	v_div_scale_f32 v42, s[16:17], v22, v22, 1.0
	v_rcp_f32_e32 v110, v42
	v_fma_f32 v111, v5, v108, 1.0
	v_fma_f32 v108, -v42, v110, 1.0
	v_fmac_f32_e32 v110, v108, v110
	v_div_scale_f32 v108, vcc, 1.0, v22, 1.0
	v_mul_f32_e32 v122, v108, v110
	v_fma_f32 v123, -v42, v122, v108
	v_fmac_f32_e32 v122, v123, v110
	v_fma_f32 v42, -v42, v122, v108
	v_div_fmas_f32 v42, v42, v110, v122
	v_div_fixup_f32 v42, v42, v22, 1.0
	v_mul_f32_e32 v108, v118, v42
	v_mul_f32_e32 v110, v119, v42
	v_pk_mul_f32 v[108:109], v[108:109], v[12:13]
	v_pk_mul_f32 v[110:111], v[110:111], v[14:15]
	v_pk_mul_f32 v[12:13], v[120:121], v[42:43]
	v_pk_fma_f32 v[14:15], v[46:47], v[112:113], s[2:3]
	v_pk_mul_f32 v[122:123], v[108:109], v[106:107] op_sel:[1,0] op_sel_hi:[0,1]
	v_mov_b32_e32 v13, v15
	v_pk_mul_f32 v[112:113], v[12:13], v[100:101]
	v_pk_mul_f32 v[12:13], v[114:115], v[42:43]
	v_pk_fma_f32 v[14:15], v[44:45], v[116:117], s[2:3]
	v_fma_f32 v22, v8, v122, 0
	v_pk_mul_f32 v[124:125], v[110:111], v[106:107]
	v_mov_b32_e32 v13, v15
	v_fmac_f32_e32 v22, v9, v125
	v_pk_mul_f32 v[130:131], v[112:113], v[104:105] op_sel:[1,0] op_sel_hi:[0,1]
	v_pk_mul_f32 v[116:117], v[12:13], v[102:103]
	v_fmac_f32_e32 v22, v10, v130
	v_pk_mul_f32 v[132:133], v[116:117], v[104:105]
	s_nop 0
	v_fmac_f32_e32 v22, v11, v133
	s_nop 1
	v_add_f32_dpp v12, v22, v22 quad_perm:[1,0,3,2] row_mask:0xf bank_mask:0xf bound_ctrl:1
	s_nop 1
	v_add_f32_dpp v12, v12, v12 quad_perm:[2,3,0,1] row_mask:0xf bank_mask:0xf bound_ctrl:1
	s_nop 1
	v_add_f32_dpp v12, v12, v12 row_ror:4 row_mask:0xf bank_mask:0xf bound_ctrl:1
	s_nop 1
	v_mov_b32_dpp v13, v12 row_ror:8 row_mask:0xf bank_mask:0xf bound_ctrl:1
.Lh1skip3:
	s_mov_b64 exec, s[98:99]
	s_waitcnt lgkmcnt(0)
	s_barrier
	s_and_saveexec_b64 s[16:17], s[14:15]
	s_xor_b64 s[16:17], exec, s[16:17]
	s_cbranch_execz .LBB0_1165
	ds_read_b128 v[12:15], v146 offset:39936
	ds_read_b128 v[104:107], v146 offset:39952
	ds_read_b128 v[108:111], v146 offset:39968
	ds_read_b128 v[112:115], v146 offset:39984
	s_mov_b32 s38, 0x3029000
	s_waitcnt lgkmcnt(3)
	v_add_f32_e32 v12, v12, v13
	v_add_f32_e32 v13, v14, v15
	v_add_f32_e32 v12, v12, v13
	s_waitcnt lgkmcnt(2)
	v_add_f32_e32 v13, v104, v105
	v_add_f32_e32 v14, v106, v107
	v_add_f32_e32 v13, v13, v14
	v_add_f32_e32 v12, v12, v13
	s_waitcnt lgkmcnt(1)
	v_add_f32_e32 v13, v108, v109
	v_add_f32_e32 v14, v110, v111
	v_add_f32_e32 v13, v13, v14
	v_add_f32_e32 v12, v12, v13
	s_waitcnt lgkmcnt(0)
	v_add_f32_e32 v13, v112, v113
	v_add_f32_e32 v14, v114, v115
	v_add_f32_e32 v13, v13, v14
	v_add_f32_e32 v12, v12, v13
	v_bfe_u32 v13, v12, 16, 1
	v_add3_u32 v22, v12, v13, s41
	v_add_co_u32_e32 v102, vcc, s38, v102
	ds_read_b128 v[12:15], v147 offset:39936
	s_nop 0
	v_addc_co_u32_e32 v103, vcc, 0, v103, vcc
	global_store_short_d16_hi v[102:103], v22, off
	ds_read_b128 v[102:105], v147 offset:39952
	ds_read_b128 v[106:109], v147 offset:39968
	ds_read_b128 v[110:113], v147 offset:39984
	s_waitcnt lgkmcnt(3)
	v_add_f32_e32 v12, v12, v13
	v_add_f32_e32 v13, v14, v15
	v_add_f32_e32 v12, v12, v13
	s_waitcnt lgkmcnt(2)
	v_add_f32_e32 v13, v102, v103
	v_add_f32_e32 v14, v104, v105
	v_add_f32_e32 v13, v13, v14
	v_add_f32_e32 v12, v12, v13
	s_waitcnt lgkmcnt(1)
	v_add_f32_e32 v13, v106, v107
	v_add_f32_e32 v14, v108, v109
	v_add_f32_e32 v13, v13, v14
	v_add_f32_e32 v12, v12, v13
	s_waitcnt lgkmcnt(0)
	v_add_f32_e32 v13, v110, v111
	v_add_f32_e32 v14, v112, v113
	v_add_f32_e32 v13, v13, v14
	v_add_f32_e32 v12, v12, v13
	v_bfe_u32 v13, v12, 16, 1
	v_add3_u32 v14, v12, v13, s41
	v_add_co_u32_e32 v12, vcc, 0x3029000, v100
	s_nop 1
	v_addc_co_u32_e32 v13, vcc, 0, v101, vcc
	global_store_short_d16_hi v[12:13], v14, off
.LBB0_1165:
	s_andn2_saveexec_b64 s[38:39], s[16:17]
	s_cbranch_execz .LBB0_1128
	s_cmpk_gt_u32 s45, 0xfb
	s_cbranch_scc1 .LBB0_1176
	s_and_saveexec_b64 s[16:17], s[8:9]
	s_cbranch_execz .LBB0_1169
	v_add_f32_e32 v12, v12, v13
	global_store_dword v[142:143], v12, off offset:1024

	.amdhsa_kernel _Z4mega6Params
		.amdhsa_group_segment_fixed_size 0
		.amdhsa_private_segment_fixed_size 0
		.amdhsa_kernarg_size 568
		.amdhsa_user_sgpr_count 2
		.amdhsa_user_sgpr_dispatch_ptr 0
		.amdhsa_user_sgpr_queue_ptr 0
		.amdhsa_user_sgpr_kernarg_segment_ptr 1
		.amdhsa_user_sgpr_dispatch_id 0
		.amdhsa_user_sgpr_kernarg_preload_length 0
		.amdhsa_user_sgpr_kernarg_preload_offset 0
		.amdhsa_user_sgpr_private_segment_size 0
		.amdhsa_uses_dynamic_stack 0
		.amdhsa_enable_private_segment 0
		.amdhsa_system_sgpr_workgroup_id_x 1
		.amdhsa_system_sgpr_workgroup_id_y 0
		.amdhsa_system_sgpr_workgroup_id_z 0
		.amdhsa_system_sgpr_workgroup_info 0
		.amdhsa_system_vgpr_workitem_id 2
		.amdhsa_next_free_vgpr 256
		.amdhsa_next_free_sgpr 100
		.amdhsa_accum_offset 256
		.amdhsa_reserve_vcc 1
		.amdhsa_float_round_mode_32 0
		.amdhsa_float_round_mode_16_64 0
		.amdhsa_float_denorm_mode_32 3
		.amdhsa_float_denorm_mode_16_64 3
		.amdhsa_dx10_clamp 1
		.amdhsa_ieee_mode 1
		.amdhsa_fp16_overflow 0
		.amdhsa_tg_split 0
		.amdhsa_exception_fp_ieee_invalid_op 0
		.amdhsa_exception_fp_denorm_src 0
		.amdhsa_exception_fp_ieee_div_zero 0
		.amdhsa_exception_fp_ieee_overflow 0
		.amdhsa_exception_fp_ieee_underflow 0
		.amdhsa_exception_fp_ieee_inexact 0
		.amdhsa_exception_int_div_zero 0
	.end_amdhsa_kernel

amdhsa.kernels:
  - .agpr_count:     0
    .args:
      - .offset:         0
        .size:           312
        .value_kind:     by_value
      - .offset:         312
        .size:           4
        .value_kind:     hidden_block_count_x
      - .offset:         316
        .size:           4
        .value_kind:     hidden_block_count_y
      - .offset:         320
        .size:           4
        .value_kind:     hidden_block_count_z
      - .offset:         324
        .size:           2
        .value_kind:     hidden_group_size_x
      - .offset:         326
        .size:           2
        .value_kind:     hidden_group_size_y
      - .offset:         328
        .size:           2
        .value_kind:     hidden_group_size_z
      - .offset:         330
        .size:           2
        .value_kind:     hidden_remainder_x
      - .offset:         332
        .size:           2
        .value_kind:     hidden_remainder_y
      - .offset:         334
        .size:           2
        .value_kind:     hidden_remainder_z
      - .offset:         352
        .size:           8
        .value_kind:     hidden_global_offset_x
      - .offset:         360
        .size:           8
        .value_kind:     hidden_global_offset_y
      - .offset:         368
        .size:           8
        .value_kind:     hidden_global_offset_z
      - .offset:         376
        .size:           2
        .value_kind:     hidden_grid_dims
      - .offset:         400
        .size:           8
        .value_kind:     hidden_multigrid_sync_arg
      - .offset:         432
        .size:           4
        .value_kind:     hidden_dynamic_lds_size
    .group_segment_fixed_size: 0
    .kernarg_segment_align: 8
    .kernarg_segment_size: 568
    .language:       OpenCL C
    .language_version:
      - 2
      - 0
    .max_flat_workgroup_size: 512
    .name:           _Z4mega6Params
    .private_segment_fixed_size: 0
    .sgpr_count:     106
    .sgpr_spill_count: 60
    .symbol:         _Z4mega6Params.kd
    .uniform_work_group_size: 1
    .uses_dynamic_stack: false
    .vgpr_count:     256
    .vgpr_spill_count: 0
    .wavefront_size: 64
